# PH1: adaLN rows dealt XCD-locally to workgroups without a filter-GEMM unit (filter units no longer wait behind adaLN)
# baseline (speedup 1.0000x reference)
.LBB0_187:
	v_readlane_b32 s8, v255, 40
	s_cmpk_gt_i32 s34, 0x5ff
	v_readlane_b32 s9, v255, 41
	v_readlane_b32 s10, v255, 42
	v_readlane_b32 s11, v255, 43
	s_waitcnt lgkmcnt(0)
	s_barrier
	v_readlane_b32 s12, v255, 44
	v_readlane_b32 s13, v255, 45
	v_readlane_b32 s14, v255, 46
	v_readlane_b32 s15, v255, 47
	v_readlane_b32 s16, v255, 48
	v_readlane_b32 s17, v255, 49
	v_readlane_b32 s18, v255, 50
	v_readlane_b32 s19, v255, 51
	v_readlane_b32 s20, v255, 52
	v_readlane_b32 s21, v255, 53
	v_readlane_b32 s22, v255, 54
	v_readlane_b32 s23, v255, 55
	s_add_i32 s0, s96, 64
	s_and_b32 s0, s0, 0xff
	s_cmp_lt_u32 s0, 0x44
	s_cbranch_scc1 .LBB0_190
	s_and_b32 s4, s96, 7
	s_lshr_b32 s5, s96, 3
	s_movk_i32 s2, 0x600
	s_cmp_lt_u32 s4, 4
	s_cselect_b32 s2, 0x5c0, s2
	s_cselect_b32 s6, 1, 0
	s_sub_i32 s5, s5, s6
	s_lshl_b32 s5, s5, 3
	s_add_i32 s5, s5, s86
	s_lshl_b32 s5, s5, 3
	s_mul_i32 s0, s4, 0x600
	s_add_i32 s98, s0, 0x600
	s_add_i32 s0, s0, s5
	s_ashr_i32 s1, s0, 31
	s_ashr_i32 s3, s2, 31
	s_movk_i32 s4, 0xfff
	v_mov_b32_e32 v129, 0
	v_mov_b32_e32 v186, 0x3727c5ac
	s_movk_i32 s5, 0x7fff
	s_mov_b32 s6, 0xffff0000
.LBB0_189:
	v_mbcnt_lo_u32_b32 v0, -1, 0
	v_mbcnt_hi_u32_b32 v0, -1, v0
	s_nop 0
	v_ashrrev_i32_e32 v2, 3, v0
	v_add_u32_e32 v1, s0, v2
	v_ashrrev_i32_e32 v3, 31, v2
	v_lshl_add_u64 v[130:131], s[0:1], 0, v[2:3]
	v_add_u32_e32 v2, 0xfffff000, v1
	v_ashrrev_i32_e32 v3, 31, v2
	v_lshlrev_b64 v[4:5], 12, v[130:131]
	v_lshlrev_b64 v[2:3], 12, v[2:3]
	v_and_b32_e32 v0, 7, v0
	v_lshlrev_b32_e32 v6, 1, v1
	v_lshl_add_u64 v[4:5], s[8:9], 0, v[4:5]
	v_lshl_add_u64 v[2:3], s[10:11], 0, v[2:3]
	v_cmp_lt_i32_e32 vcc, s4, v1
	v_lshlrev_b32_e32 v128, 4, v0
	v_and_b32_e32 v6, 0xffffe000, v6
	v_cndmask_b32_e32 v3, v5, v3, vcc
	v_cndmask_b32_e32 v2, v4, v2, vcc
	v_cndmask_b32_e32 v1, 0, v6, vcc
	v_lshl_add_u64 v[4:5], v[2:3], 0, v[128:129]
	v_add3_u32 v187, 0, v1, v128
	v_lshlrev_b32_e32 v128, 3, v0
	global_load_dwordx4 v[124:127], v[4:5], off
	global_load_dwordx4 v[120:123], v[4:5], off offset:128
	global_load_dwordx4 v[116:119], v[4:5], off offset:256
	global_load_dwordx4 v[108:111], v[4:5], off offset:384
	global_load_dwordx4 v[112:115], v[4:5], off offset:512
	global_load_dwordx4 v[104:107], v[4:5], off offset:640
	global_load_dwordx4 v[96:99], v[4:5], off offset:768
	global_load_dwordx4 v[100:103], v[4:5], off offset:896
	global_load_dwordx4 v[92:95], v[4:5], off offset:1024
	global_load_dwordx4 v[84:87], v[4:5], off offset:1152
	global_load_dwordx4 v[88:91], v[4:5], off offset:1280
	global_load_dwordx4 v[80:83], v[4:5], off offset:1408
	global_load_dwordx4 v[72:75], v[4:5], off offset:1536
	global_load_dwordx4 v[76:79], v[4:5], off offset:1664
	global_load_dwordx4 v[68:71], v[4:5], off offset:1792
	global_load_dwordx4 v[60:63], v[4:5], off offset:1920
	global_load_dwordx4 v[64:67], v[4:5], off offset:2048
	global_load_dwordx4 v[56:59], v[4:5], off offset:2176
	global_load_dwordx4 v[48:51], v[4:5], off offset:2304
	global_load_dwordx4 v[52:55], v[4:5], off offset:2432
	global_load_dwordx4 v[44:47], v[4:5], off offset:2560
	global_load_dwordx4 v[36:39], v[4:5], off offset:2688
	global_load_dwordx4 v[40:43], v[4:5], off offset:2816
	global_load_dwordx4 v[32:35], v[4:5], off offset:2944
	global_load_dwordx4 v[24:27], v[4:5], off offset:3072
	global_load_dwordx4 v[28:31], v[4:5], off offset:3200
	global_load_dwordx4 v[20:23], v[4:5], off offset:3328
	global_load_dwordx4 v[12:15], v[4:5], off offset:3456
	global_load_dwordx4 v[16:19], v[4:5], off offset:3584
	global_load_dwordx4 v[8:11], v[4:5], off offset:3712
	global_load_dwordx4 v[0:3], v[4:5], off offset:3840
	s_nop 0
	global_load_dwordx4 v[4:7], v[4:5], off offset:3968
	ds_read_b128 v[134:137], v187 offset:4096
	ds_read_b128 v[138:141], v187 offset:4224
	ds_read_b128 v[142:145], v187 offset:4352
	ds_read_b128 v[146:149], v187 offset:4480
	v_lshlrev_b64 v[130:131], 11, v[130:131]
	s_waitcnt lgkmcnt(3)
	v_pk_add_f32 v[132:133], v[136:137], 1.0 op_sel_hi:[1,0]
	s_waitcnt lgkmcnt(2)
	v_pk_add_f32 v[136:137], v[140:141], 1.0 op_sel_hi:[1,0]
	s_waitcnt lgkmcnt(1)
	v_pk_add_f32 v[140:141], v[144:145], 1.0 op_sel_hi:[1,0]
	s_waitcnt lgkmcnt(0)
	v_pk_add_f32 v[144:145], v[148:149], 1.0 op_sel_hi:[1,0]
	v_lshl_add_u64 v[130:131], s[60:61], 0, v[130:131]
	v_lshl_add_u64 v[130:131], v[130:131], 0, v[128:129]
	v_pk_add_f32 v[134:135], v[134:135], 1.0 op_sel_hi:[1,0]
	v_pk_add_f32 v[138:139], v[138:139], 1.0 op_sel_hi:[1,0]
	v_pk_add_f32 v[142:143], v[142:143], 1.0 op_sel_hi:[1,0]
	v_pk_add_f32 v[146:147], v[146:147], 1.0 op_sel_hi:[1,0]
	s_add_u32 s0, s0, s2
	s_addc_u32 s1, s1, s3
	s_cmp_ge_i32 s0, s98
	s_waitcnt vmcnt(31)
	v_mov_b32_e32 v148, v124
	s_waitcnt vmcnt(30)
	v_mov_b32_e32 v149, v120
	v_mov_b32_e32 v150, v125
	v_mov_b32_e32 v151, v121
	v_mov_b32_e32 v152, v126
	v_mov_b32_e32 v153, v122
	v_mov_b32_e32 v154, v127
	v_mov_b32_e32 v155, v123
	s_waitcnt vmcnt(29)
	v_mov_b32_e32 v156, v117
	v_mov_b32_e32 v157, v118
	v_mov_b32_e32 v158, v116
	v_mov_b32_e32 v159, v119
	v_pk_add_f32 v[148:149], v[148:149], v[150:151]
	v_pk_add_f32 v[150:151], v[152:153], v[154:155]
	v_pk_add_f32 v[152:153], v[156:157], v[158:159]
	v_pk_add_f32 v[148:149], v[148:149], v[150:151]
	v_pk_add_f32 v[150:151], v[152:153], v[152:153] op_sel:[0,1] op_sel_hi:[1,0]
	v_add_f32_e32 v148, 0, v148
	s_waitcnt vmcnt(28)
	v_add_f32_e32 v160, v108, v109
	v_add_f32_e32 v162, v110, v111
	s_waitcnt vmcnt(27)
	v_mov_b32_e32 v165, v112
	v_mov_b32_e32 v161, v114
	v_mov_b32_e32 v163, v115
	v_mov_b32_e32 v151, v113
	v_add_f32_e32 v164, v148, v149
	s_waitcnt vmcnt(26)
	v_mov_b32_e32 v166, v105
	v_mov_b32_e32 v167, v106
	v_mov_b32_e32 v168, v104
	v_mov_b32_e32 v169, v107
	v_pk_add_f32 v[154:155], v[160:161], v[162:163]
	v_pk_add_f32 v[148:149], v[164:165], v[150:151]
	v_pk_add_f32 v[156:157], v[166:167], v[168:169]
	v_pk_add_f32 v[148:149], v[148:149], v[154:155]
	v_pk_add_f32 v[152:153], v[156:157], v[156:157] op_sel:[0,1] op_sel_hi:[1,0]
	v_pk_add_f32 v[148:149], v[148:149], v[148:149] op_sel:[0,1] op_sel_hi:[1,0]
	s_waitcnt vmcnt(25)
	v_add_f32_e32 v170, v96, v97
	v_add_f32_e32 v172, v98, v99
	s_waitcnt vmcnt(24)
	v_mov_b32_e32 v171, v102
	v_mov_b32_e32 v173, v103
	v_mov_b32_e32 v153, v101
	v_mov_b32_e32 v149, v100
	s_waitcnt vmcnt(23)
	v_mov_b32_e32 v174, v93
	v_mov_b32_e32 v175, v94
	v_mov_b32_e32 v176, v92
	v_mov_b32_e32 v177, v95
	v_pk_add_f32 v[158:159], v[170:171], v[172:173]
	v_pk_add_f32 v[148:149], v[148:149], v[152:153]
	v_pk_add_f32 v[160:161], v[174:175], v[176:177]
	v_pk_add_f32 v[148:149], v[148:149], v[158:159]
	v_pk_add_f32 v[156:157], v[160:161], v[160:161] op_sel:[0,1] op_sel_hi:[1,0]
	v_pk_add_f32 v[148:149], v[148:149], v[148:149] op_sel:[0,1] op_sel_hi:[1,0]
	s_waitcnt vmcnt(22)
	v_add_f32_e32 v178, v84, v85
	v_add_f32_e32 v180, v86, v87
	s_waitcnt vmcnt(21)
	v_mov_b32_e32 v179, v90
	v_mov_b32_e32 v181, v91
	v_mov_b32_e32 v157, v89
	v_mov_b32_e32 v149, v88
	s_waitcnt vmcnt(20)
	v_mov_b32_e32 v182, v81
	v_mov_b32_e32 v183, v82
	v_mov_b32_e32 v184, v80
	v_mov_b32_e32 v185, v83
	v_pk_add_f32 v[162:163], v[178:179], v[180:181]
	v_pk_add_f32 v[148:149], v[148:149], v[156:157]
	v_pk_add_f32 v[166:167], v[182:183], v[184:185]
	v_pk_add_f32 v[148:149], v[148:149], v[162:163]
	v_pk_add_f32 v[160:161], v[166:167], v[166:167] op_sel:[0,1] op_sel_hi:[1,0]
	v_pk_add_f32 v[148:149], v[148:149], v[148:149] op_sel:[0,1] op_sel_hi:[1,0]
	s_waitcnt vmcnt(19)
	v_add_f32_e32 v188, v72, v73
	v_add_f32_e32 v190, v74, v75
	s_waitcnt vmcnt(18)
	v_mov_b32_e32 v189, v78
	v_mov_b32_e32 v191, v79
	v_mov_b32_e32 v161, v77
	v_mov_b32_e32 v149, v76
	s_waitcnt vmcnt(17)
	v_mov_b32_e32 v192, v69
	v_mov_b32_e32 v193, v70
	v_mov_b32_e32 v194, v68
	v_mov_b32_e32 v195, v71
	v_pk_add_f32 v[168:169], v[188:189], v[190:191]
	v_pk_add_f32 v[148:149], v[148:149], v[160:161]
	v_pk_add_f32 v[170:171], v[192:193], v[194:195]
	v_pk_add_f32 v[148:149], v[148:149], v[168:169]
	v_pk_add_f32 v[166:167], v[170:171], v[170:171] op_sel:[0,1] op_sel_hi:[1,0]
	v_pk_add_f32 v[148:149], v[148:149], v[148:149] op_sel:[0,1] op_sel_hi:[1,0]
	s_waitcnt vmcnt(16)
	v_add_f32_e32 v196, v60, v61
	v_add_f32_e32 v198, v62, v63
	s_waitcnt vmcnt(15)
	v_mov_b32_e32 v197, v66
	v_mov_b32_e32 v199, v67
	v_mov_b32_e32 v167, v65
	v_mov_b32_e32 v149, v64
	s_waitcnt vmcnt(14)
	v_mov_b32_e32 v200, v57
	v_mov_b32_e32 v201, v58
	v_mov_b32_e32 v202, v56
	v_mov_b32_e32 v203, v59
	v_pk_add_f32 v[172:173], v[196:197], v[198:199]
	v_pk_add_f32 v[148:149], v[148:149], v[166:167]
	v_pk_add_f32 v[174:175], v[200:201], v[202:203]
	v_pk_add_f32 v[148:149], v[148:149], v[172:173]
	v_pk_add_f32 v[170:171], v[174:175], v[174:175] op_sel:[0,1] op_sel_hi:[1,0]
	v_pk_add_f32 v[148:149], v[148:149], v[148:149] op_sel:[0,1] op_sel_hi:[1,0]
	s_waitcnt vmcnt(13)
	v_add_f32_e32 v204, v48, v49
	v_add_f32_e32 v206, v50, v51
	s_waitcnt vmcnt(12)
	v_mov_b32_e32 v205, v54
	v_mov_b32_e32 v207, v55
	v_mov_b32_e32 v171, v53
	v_mov_b32_e32 v149, v52
	s_waitcnt vmcnt(11)
	v_mov_b32_e32 v208, v45
	v_mov_b32_e32 v209, v46
	v_mov_b32_e32 v210, v44
	v_mov_b32_e32 v211, v47
	v_pk_add_f32 v[176:177], v[204:205], v[206:207]
	v_pk_add_f32 v[148:149], v[148:149], v[170:171]
	v_pk_add_f32 v[178:179], v[208:209], v[210:211]
	v_pk_add_f32 v[148:149], v[148:149], v[176:177]
	v_pk_add_f32 v[174:175], v[178:179], v[178:179] op_sel:[0,1] op_sel_hi:[1,0]
	v_pk_add_f32 v[148:149], v[148:149], v[148:149] op_sel:[0,1] op_sel_hi:[1,0]
	s_waitcnt vmcnt(10)
	v_add_f32_e32 v212, v36, v37
	v_add_f32_e32 v214, v38, v39
	s_waitcnt vmcnt(9)
	v_mov_b32_e32 v213, v42
	v_mov_b32_e32 v215, v43
	v_mov_b32_e32 v175, v41
	v_mov_b32_e32 v149, v40
	s_waitcnt vmcnt(8)
	v_mov_b32_e32 v216, v33
	v_mov_b32_e32 v217, v34
	v_mov_b32_e32 v218, v32
	v_mov_b32_e32 v219, v35
	v_pk_add_f32 v[180:181], v[212:213], v[214:215]
	v_pk_add_f32 v[148:149], v[148:149], v[174:175]
	v_pk_add_f32 v[182:183], v[216:217], v[218:219]
	v_pk_add_f32 v[148:149], v[148:149], v[180:181]
	v_pk_add_f32 v[178:179], v[182:183], v[182:183] op_sel:[0,1] op_sel_hi:[1,0]
	v_pk_add_f32 v[148:149], v[148:149], v[148:149] op_sel:[0,1] op_sel_hi:[1,0]
	s_waitcnt vmcnt(7)
	v_add_f32_e32 v220, v24, v25
	v_add_f32_e32 v222, v26, v27
	s_waitcnt vmcnt(6)
	v_mov_b32_e32 v221, v30
	v_mov_b32_e32 v223, v31
	v_mov_b32_e32 v179, v29
	v_mov_b32_e32 v149, v28
	s_waitcnt vmcnt(5)
	v_mov_b32_e32 v224, v21
	v_mov_b32_e32 v225, v22
	v_mov_b32_e32 v226, v20
	v_mov_b32_e32 v227, v23
	v_pk_add_f32 v[184:185], v[220:221], v[222:223]
	v_pk_add_f32 v[148:149], v[148:149], v[178:179]
	v_pk_add_f32 v[188:189], v[224:225], v[226:227]
	v_pk_add_f32 v[148:149], v[148:149], v[184:185]
	v_pk_add_f32 v[182:183], v[188:189], v[188:189] op_sel:[0,1] op_sel_hi:[1,0]
	v_pk_add_f32 v[148:149], v[148:149], v[148:149] op_sel:[0,1] op_sel_hi:[1,0]
	s_waitcnt vmcnt(4)
	v_add_f32_e32 v228, v12, v13
	v_add_f32_e32 v230, v14, v15
	s_waitcnt vmcnt(3)
	v_mov_b32_e32 v229, v18
	v_mov_b32_e32 v231, v19
	v_mov_b32_e32 v183, v17
	v_mov_b32_e32 v149, v16
	s_waitcnt vmcnt(2)
	v_mov_b32_e32 v232, v9
	v_mov_b32_e32 v233, v10
	v_mov_b32_e32 v234, v8
	v_mov_b32_e32 v235, v11
	v_pk_add_f32 v[190:191], v[228:229], v[230:231]
	v_pk_add_f32 v[148:149], v[148:149], v[182:183]
	v_pk_add_f32 v[192:193], v[232:233], v[234:235]
	v_pk_add_f32 v[148:149], v[148:149], v[190:191]
	v_pk_add_f32 v[188:189], v[192:193], v[192:193] op_sel:[0,1] op_sel_hi:[1,0]
	v_pk_add_f32 v[148:149], v[148:149], v[148:149] op_sel:[0,1] op_sel_hi:[1,0]
	s_waitcnt vmcnt(1)
	v_add_f32_e32 v236, v0, v1
	v_add_f32_e32 v238, v2, v3
	s_waitcnt vmcnt(0)
	v_mov_b32_e32 v237, v6
	v_mov_b32_e32 v239, v7
	v_mov_b32_e32 v189, v5
	v_mov_b32_e32 v149, v4
	v_pk_add_f32 v[194:195], v[236:237], v[238:239]
	v_pk_add_f32 v[148:149], v[148:149], v[188:189]
	s_nop 0
	v_pk_add_f32 v[148:149], v[148:149], v[194:195]
	s_nop 0
	v_add_f32_e32 v148, v148, v149
	s_nop 1
	v_add_f32_dpp v148, v148, v148 quad_perm:[1,0,3,2] row_mask:0xf bank_mask:0xf bound_ctrl:1
	s_nop 1
	v_add_f32_dpp v148, v148, v148 quad_perm:[2,3,0,1] row_mask:0xf bank_mask:0xf bound_ctrl:1
	s_nop 1
	v_add_f32_dpp v201, v148, v148 row_half_mirror row_mask:0xf bank_mask:0xf bound_ctrl:1
	v_fmamk_f32 v125, v201, 0xba800000, v125
	v_fmamk_f32 v121, v201, 0xba800000, v121
	v_fmamk_f32 v117, v201, 0xba800000, v117
	v_fmamk_f32 v116, v201, 0xba800000, v116
	v_fmamk_f32 v119, v201, 0xba800000, v119
	v_fmac_f32_e32 v118, 0xba800000, v201
	v_fmamk_f32 v69, v201, 0xba800000, v69
	v_fmamk_f32 v68, v201, 0xba800000, v68
	v_fmamk_f32 v71, v201, 0xba800000, v71
	v_fmac_f32_e32 v70, 0xba800000, v201
	v_fmamk_f32 v57, v201, 0xba800000, v57
	v_fmamk_f32 v56, v201, 0xba800000, v56
	v_fmamk_f32 v59, v201, 0xba800000, v59
	v_fmac_f32_e32 v58, 0xba800000, v201
	v_fmamk_f32 v45, v201, 0xba800000, v45
	v_fmamk_f32 v44, v201, 0xba800000, v44
	v_fmamk_f32 v47, v201, 0xba800000, v47
	v_fmac_f32_e32 v46, 0xba800000, v201
	v_fmamk_f32 v33, v201, 0xba800000, v33
	v_fmamk_f32 v32, v201, 0xba800000, v32
	v_fmamk_f32 v35, v201, 0xba800000, v35
	v_fmac_f32_e32 v34, 0xba800000, v201
	v_fmamk_f32 v21, v201, 0xba800000, v21
	v_fmamk_f32 v20, v201, 0xba800000, v20
	v_fmamk_f32 v23, v201, 0xba800000, v23
	v_fmac_f32_e32 v22, 0xba800000, v201
	v_fmac_f32_e32 v124, 0xba800000, v201
	v_fmac_f32_e32 v120, 0xba800000, v201
	v_fmamk_f32 v108, v201, 0xba800000, v108
	v_fmac_f32_e32 v110, 0xba800000, v201
	v_fmamk_f32 v105, v201, 0xba800000, v105
	v_fmamk_f32 v104, v201, 0xba800000, v104
	v_fmamk_f32 v107, v201, 0xba800000, v107
	v_fmac_f32_e32 v106, 0xba800000, v201
	v_fmamk_f32 v93, v201, 0xba800000, v93
	v_fmamk_f32 v92, v201, 0xba800000, v92
	v_fmamk_f32 v95, v201, 0xba800000, v95
	v_fmac_f32_e32 v94, 0xba800000, v201
	v_fmamk_f32 v81, v201, 0xba800000, v81
	v_fmamk_f32 v80, v201, 0xba800000, v80
	v_fmamk_f32 v83, v201, 0xba800000, v83
	v_fmac_f32_e32 v82, 0xba800000, v201
	v_fmamk_f32 v9, v201, 0xba800000, v9
	v_fmamk_f32 v8, v201, 0xba800000, v8
	v_fmamk_f32 v11, v201, 0xba800000, v11
	v_fmac_f32_e32 v10, 0xba800000, v201
	v_mov_b32_e32 v150, v125
	v_mov_b32_e32 v151, v121
	v_pk_mul_f32 v[152:153], v[118:119], v[118:119]
	v_pk_mul_f32 v[154:155], v[116:117], v[116:117]
	v_pk_mul_f32 v[168:169], v[70:71], v[70:71]
	v_pk_mul_f32 v[170:171], v[68:69], v[68:69]
	v_pk_mul_f32 v[172:173], v[58:59], v[58:59]
	v_pk_mul_f32 v[174:175], v[56:57], v[56:57]
	v_pk_mul_f32 v[176:177], v[46:47], v[46:47]
	v_pk_mul_f32 v[178:179], v[44:45], v[44:45]
	v_pk_mul_f32 v[180:181], v[34:35], v[34:35]
	v_pk_mul_f32 v[182:183], v[32:33], v[32:33]
	v_pk_mul_f32 v[184:185], v[22:23], v[22:23]
	v_pk_mul_f32 v[188:189], v[20:21], v[20:21]
	v_fmamk_f32 v109, v201, 0xba800000, v109
	v_fmamk_f32 v111, v201, 0xba800000, v111
	v_mov_b32_e32 v148, v124
	v_mov_b32_e32 v149, v120
	v_pk_mul_f32 v[156:157], v[106:107], v[106:107]
	v_pk_mul_f32 v[158:159], v[104:105], v[104:105]
	v_pk_mul_f32 v[160:161], v[94:95], v[94:95]
	v_pk_mul_f32 v[162:163], v[92:93], v[92:93]
	v_pk_mul_f32 v[164:165], v[82:83], v[82:83]
	v_pk_mul_f32 v[166:167], v[80:81], v[80:81]
	v_pk_mul_f32 v[190:191], v[10:11], v[10:11]
	v_pk_mul_f32 v[192:193], v[8:9], v[8:9]
	v_pk_mov_b32 v[194:195], v[154:155], v[152:153] op_sel:[1,0]
	v_mov_b32_e32 v155, v153
	v_pk_mov_b32 v[196:197], v[170:171], v[168:169] op_sel:[1,0]
	v_mov_b32_e32 v171, v169
	v_pk_mov_b32 v[168:169], v[174:175], v[172:173] op_sel:[1,0]
	v_mov_b32_e32 v175, v173
	v_pk_mov_b32 v[172:173], v[178:179], v[176:177] op_sel:[1,0]
	v_mov_b32_e32 v179, v177
	v_pk_mov_b32 v[176:177], v[182:183], v[180:181] op_sel:[1,0]
	v_mov_b32_e32 v183, v181
	v_pk_mov_b32 v[180:181], v[188:189], v[184:185] op_sel:[1,0]
	v_mov_b32_e32 v189, v185
	v_pk_mul_f32 v[150:151], v[150:151], v[150:151]
	v_mul_f32_e32 v200, v108, v108
	v_mul_f32_e32 v202, v110, v110
	v_fmamk_f32 v127, v201, 0xba800000, v127
	v_fmamk_f32 v123, v201, 0xba800000, v123
	v_fmamk_f32 v113, v201, 0xba800000, v113
	v_fmac_f32_e32 v112, 0xba800000, v201
	v_fmamk_f32 v96, v201, 0xba800000, v96
	v_fmac_f32_e32 v98, 0xba800000, v201
	v_pk_mov_b32 v[152:153], v[158:159], v[156:157] op_sel:[1,0]
	v_mov_b32_e32 v159, v157
	v_pk_mov_b32 v[156:157], v[162:163], v[160:161] op_sel:[1,0]
	v_mov_b32_e32 v163, v161
	v_pk_mov_b32 v[160:161], v[166:167], v[164:165] op_sel:[1,0]
	v_mov_b32_e32 v167, v165
	v_pk_mov_b32 v[184:185], v[192:193], v[190:191] op_sel:[1,0]
	v_mov_b32_e32 v193, v191
	v_pk_fma_f32 v[190:191], v[148:149], v[148:149], v[150:151]
	v_pk_add_f32 v[194:195], v[194:195], v[154:155]
	v_pk_add_f32 v[150:151], v[172:173], v[178:179]
	v_pk_add_f32 v[154:155], v[180:181], v[188:189]
	v_pk_fma_f32 v[178:179], v[108:109], v[108:109], v[200:201] op_sel_hi:[1,1,0]
	v_pk_fma_f32 v[180:181], v[110:111], v[110:111], v[202:203] op_sel_hi:[1,1,0]
	v_fmamk_f32 v126, v201, 0xba800000, v126
	v_fmamk_f32 v122, v201, 0xba800000, v122
	v_fmamk_f32 v97, v201, 0xba800000, v97
	v_fmamk_f32 v99, v201, 0xba800000, v99
	v_mov_b32_e32 v148, v127
	v_mov_b32_e32 v149, v123
	v_mul_f32_e32 v204, v96, v96
	v_pk_add_f32 v[160:161], v[160:161], v[166:167]
	v_mul_f32_e32 v166, v98, v98
	v_mul_f32_e32 v178, v112, v112
	v_mul_f32_e32 v180, v113, v113
	v_fmamk_f32 v101, v201, 0xba800000, v101
	v_fmac_f32_e32 v100, 0xba800000, v201
	v_fmamk_f32 v84, v201, 0xba800000, v84
	v_fmac_f32_e32 v86, 0xba800000, v201
	v_mov_b32_e32 v164, v126
	v_mov_b32_e32 v165, v122
	v_pk_mul_f32 v[148:149], v[148:149], v[148:149]
	v_pk_add_f32 v[162:163], v[156:157], v[162:163]
	v_pk_add_f32 v[156:157], v[184:185], v[192:193]
	v_pk_add_f32 v[192:193], v[178:179], v[180:181]
	v_pk_fma_f32 v[178:179], v[96:97], v[96:97], v[204:205] op_sel_hi:[1,1,0]
	v_pk_fma_f32 v[166:167], v[98:99], v[98:99], v[166:167] op_sel_hi:[1,1,0]
	v_fmamk_f32 v85, v201, 0xba800000, v85
	v_fmamk_f32 v87, v201, 0xba800000, v87
	v_pk_fma_f32 v[198:199], v[164:165], v[164:165], v[148:149]
	v_pk_add_f32 v[164:165], v[152:153], v[158:159]
	v_pk_add_f32 v[158:159], v[196:197], v[170:171]
	v_mul_f32_e32 v170, v84, v84
	v_pk_add_f32 v[148:149], v[168:169], v[174:175]
	v_mul_f32_e32 v168, v86, v86
	v_mul_f32_e32 v178, v100, v100
	v_mul_f32_e32 v166, v101, v101
	v_fmamk_f32 v89, v201, 0xba800000, v89
	v_fmac_f32_e32 v88, 0xba800000, v201
	v_fmamk_f32 v72, v201, 0xba800000, v72
	v_fmac_f32_e32 v74, 0xba800000, v201
	v_pk_add_f32 v[152:153], v[176:177], v[182:183]
	v_pk_add_f32 v[182:183], v[178:179], v[166:167]
	v_pk_fma_f32 v[166:167], v[84:85], v[84:85], v[170:171] op_sel_hi:[1,1,0]
	v_pk_fma_f32 v[168:169], v[86:87], v[86:87], v[168:169] op_sel_hi:[1,1,0]
	v_fmamk_f32 v73, v201, 0xba800000, v73
	v_fmamk_f32 v75, v201, 0xba800000, v75
	v_mul_f32_e32 v172, v72, v72
	v_mul_f32_e32 v174, v74, v74
	v_mul_f32_e32 v166, v88, v88
	v_mul_f32_e32 v168, v89, v89
	v_fmamk_f32 v77, v201, 0xba800000, v77
	v_fmac_f32_e32 v76, 0xba800000, v201
	v_fmamk_f32 v60, v201, 0xba800000, v60
	v_fmac_f32_e32 v62, 0xba800000, v201
	v_pk_add_f32 v[180:181], v[166:167], v[168:169]
	v_pk_fma_f32 v[166:167], v[72:73], v[72:73], v[172:173] op_sel_hi:[1,1,0]
	v_pk_fma_f32 v[170:171], v[74:75], v[74:75], v[174:175] op_sel_hi:[1,1,0]
	v_fmamk_f32 v61, v201, 0xba800000, v61
	v_fmamk_f32 v63, v201, 0xba800000, v63
	v_mul_f32_e32 v176, v60, v60
	v_mul_f32_e32 v184, v62, v62
	v_mul_f32_e32 v166, v76, v76
	v_mul_f32_e32 v170, v77, v77
	v_fmamk_f32 v65, v201, 0xba800000, v65
	v_fmac_f32_e32 v64, 0xba800000, v201
	v_fmamk_f32 v48, v201, 0xba800000, v48
	v_fmac_f32_e32 v50, 0xba800000, v201
	v_fmamk_f32 v36, v201, 0xba800000, v36
	v_fmac_f32_e32 v38, 0xba800000, v201
	v_pk_add_f32 v[178:179], v[166:167], v[170:171]
	v_pk_fma_f32 v[166:167], v[60:61], v[60:61], v[176:177] op_sel_hi:[1,1,0]
	v_pk_fma_f32 v[172:173], v[62:63], v[62:63], v[184:185] op_sel_hi:[1,1,0]
	v_fmamk_f32 v49, v201, 0xba800000, v49
	v_fmamk_f32 v51, v201, 0xba800000, v51
	v_fmamk_f32 v37, v201, 0xba800000, v37
	v_fmamk_f32 v39, v201, 0xba800000, v39
	v_fmamk_f32 v24, v201, 0xba800000, v24
	v_fmac_f32_e32 v26, 0xba800000, v201
	v_pk_add_f32 v[188:189], v[190:191], v[198:199]
	v_mul_f32_e32 v190, v48, v48
	v_mul_f32_e32 v196, v50, v50
	v_mul_f32_e32 v198, v36, v36
	v_mul_f32_e32 v168, v38, v38
	v_mul_f32_e32 v166, v64, v64
	v_mul_f32_e32 v172, v65, v65
	v_fmamk_f32 v53, v201, 0xba800000, v53
	v_fmac_f32_e32 v52, 0xba800000, v201
	v_fmamk_f32 v41, v201, 0xba800000, v41
	v_fmac_f32_e32 v40, 0xba800000, v201
	v_fmamk_f32 v25, v201, 0xba800000, v25
	v_fmamk_f32 v27, v201, 0xba800000, v27
	v_mul_f32_e32 v170, v24, v24
	v_pk_add_f32 v[176:177], v[166:167], v[172:173]
	v_mul_f32_e32 v172, v26, v26
	v_pk_fma_f32 v[166:167], v[48:49], v[48:49], v[190:191] op_sel_hi:[1,1,0]
	v_pk_fma_f32 v[174:175], v[50:51], v[50:51], v[196:197] op_sel_hi:[1,1,0]
	v_pk_fma_f32 v[184:185], v[36:37], v[36:37], v[198:199] op_sel_hi:[1,1,0]
	v_pk_fma_f32 v[168:169], v[38:39], v[38:39], v[168:169] op_sel_hi:[1,1,0]
	v_fmamk_f32 v29, v201, 0xba800000, v29
	v_fmac_f32_e32 v28, 0xba800000, v201
	v_fmamk_f32 v12, v201, 0xba800000, v12
	v_fmac_f32_e32 v14, 0xba800000, v201
	v_mul_f32_e32 v166, v52, v52
	v_mul_f32_e32 v174, v53, v53
	v_mul_f32_e32 v184, v40, v40
	v_mul_f32_e32 v168, v41, v41
	v_pk_fma_f32 v[170:171], v[24:25], v[24:25], v[170:171] op_sel_hi:[1,1,0]
	v_pk_fma_f32 v[172:173], v[26:27], v[26:27], v[172:173] op_sel_hi:[1,1,0]
	v_fmamk_f32 v13, v201, 0xba800000, v13
	v_fmamk_f32 v15, v201, 0xba800000, v15
	v_pk_add_f32 v[166:167], v[166:167], v[174:175]
	v_mul_f32_e32 v174, v12, v12
	v_pk_add_f32 v[168:169], v[184:185], v[168:169]
	v_mul_f32_e32 v184, v14, v14
	v_mul_f32_e32 v170, v28, v28
	v_mul_f32_e32 v172, v29, v29
	v_fmamk_f32 v17, v201, 0xba800000, v17
	v_fmac_f32_e32 v16, 0xba800000, v201
	v_pk_add_f32 v[170:171], v[170:171], v[172:173]
	v_pk_fma_f32 v[172:173], v[12:13], v[12:13], v[174:175] op_sel_hi:[1,1,0]
	v_pk_fma_f32 v[174:175], v[14:15], v[14:15], v[184:185] op_sel_hi:[1,1,0]
	v_fmamk_f32 v0, v201, 0xba800000, v0
	v_fmac_f32_e32 v2, 0xba800000, v201
	v_mul_f32_e32 v172, v16, v16
	v_mul_f32_e32 v174, v17, v17
	v_fmamk_f32 v1, v201, 0xba800000, v1
	v_fmamk_f32 v3, v201, 0xba800000, v3
	v_mul_f32_e32 v190, v0, v0
	v_pk_add_f32 v[172:173], v[172:173], v[174:175]
	v_mul_f32_e32 v174, v2, v2
	v_fmamk_f32 v5, v201, 0xba800000, v5
	v_fmac_f32_e32 v4, 0xba800000, v201
	v_pk_fma_f32 v[184:185], v[0:1], v[0:1], v[190:191] op_sel_hi:[1,1,0]
	v_pk_fma_f32 v[174:175], v[2:3], v[2:3], v[174:175] op_sel_hi:[1,1,0]
	v_mul_f32_e32 v184, v4, v4
	v_mul_f32_e32 v174, v5, v5
	v_fmamk_f32 v115, v201, 0xba800000, v115
	v_fmamk_f32 v114, v201, 0xba800000, v114
	v_pk_add_f32 v[174:175], v[184:185], v[174:175]
	v_pk_add_f32 v[184:185], v[194:195], v[194:195] op_sel_hi:[0,1]
	v_pk_add_f32 v[188:189], v[188:189], v[188:189] op_sel_hi:[0,1]
	v_mul_f32_e32 v184, v114, v114
	v_mul_f32_e32 v188, v115, v115
	v_pk_add_f32 v[184:185], v[184:185], v[188:189]
	v_fmamk_f32 v103, v201, 0xba800000, v103
	v_pk_add_f32 v[184:185], v[192:193], v[184:185]
	v_fmamk_f32 v102, v201, 0xba800000, v102
	v_pk_add_f32 v[164:165], v[164:165], v[164:165] op_sel_hi:[0,1]
	v_pk_add_f32 v[184:185], v[184:185], v[184:185] op_sel_hi:[0,1]
	v_mul_f32_e32 v164, v102, v102
	v_mul_f32_e32 v184, v103, v103
	v_pk_add_f32 v[164:165], v[164:165], v[184:185]
	v_fmamk_f32 v91, v201, 0xba800000, v91
	v_pk_add_f32 v[164:165], v[182:183], v[164:165]
	v_fmamk_f32 v90, v201, 0xba800000, v90
	v_pk_add_f32 v[162:163], v[162:163], v[162:163] op_sel_hi:[0,1]
	v_pk_add_f32 v[164:165], v[164:165], v[164:165] op_sel_hi:[0,1]
	v_mul_f32_e32 v162, v90, v90
	v_mul_f32_e32 v164, v91, v91
	v_pk_add_f32 v[162:163], v[162:163], v[164:165]
	v_fmamk_f32 v79, v201, 0xba800000, v79
	v_pk_add_f32 v[180:181], v[180:181], v[162:163]
	v_fmamk_f32 v78, v201, 0xba800000, v78
	v_pk_add_f32 v[160:161], v[160:161], v[160:161] op_sel_hi:[0,1]
	v_pk_add_f32 v[180:181], v[180:181], v[180:181] op_sel_hi:[0,1]
	v_mul_f32_e32 v160, v78, v78
	v_mul_f32_e32 v180, v79, v79
	v_pk_add_f32 v[160:161], v[160:161], v[180:181]
	v_fmamk_f32 v67, v201, 0xba800000, v67
	v_pk_add_f32 v[160:161], v[178:179], v[160:161]
	v_fmamk_f32 v66, v201, 0xba800000, v66
	v_pk_add_f32 v[158:159], v[158:159], v[158:159] op_sel_hi:[0,1]
	v_pk_add_f32 v[160:161], v[160:161], v[160:161] op_sel_hi:[0,1]
	v_mul_f32_e32 v158, v66, v66
	v_mul_f32_e32 v160, v67, v67
	v_pk_add_f32 v[158:159], v[158:159], v[160:161]
	v_fmamk_f32 v55, v201, 0xba800000, v55
	v_pk_add_f32 v[176:177], v[176:177], v[158:159]
	v_fmamk_f32 v54, v201, 0xba800000, v54
	v_pk_add_f32 v[148:149], v[148:149], v[148:149] op_sel_hi:[0,1]
	v_pk_add_f32 v[176:177], v[176:177], v[176:177] op_sel_hi:[0,1]
	v_mul_f32_e32 v148, v54, v54
	v_mul_f32_e32 v176, v55, v55
	v_pk_add_f32 v[148:149], v[148:149], v[176:177]
	v_fmamk_f32 v43, v201, 0xba800000, v43
	v_pk_add_f32 v[148:149], v[166:167], v[148:149]
	v_fmamk_f32 v42, v201, 0xba800000, v42
	v_pk_add_f32 v[150:151], v[150:151], v[150:151] op_sel_hi:[0,1]
	v_pk_add_f32 v[148:149], v[148:149], v[148:149] op_sel_hi:[0,1]
	v_mul_f32_e32 v150, v42, v42
	v_mul_f32_e32 v148, v43, v43
	v_pk_add_f32 v[148:149], v[150:151], v[148:149]
	v_fmamk_f32 v31, v201, 0xba800000, v31
	v_pk_add_f32 v[148:149], v[168:169], v[148:149]
	v_fmamk_f32 v30, v201, 0xba800000, v30
	v_pk_add_f32 v[152:153], v[152:153], v[152:153] op_sel_hi:[0,1]
	v_pk_add_f32 v[148:149], v[148:149], v[148:149] op_sel_hi:[0,1]
	v_mul_f32_e32 v152, v30, v30
	v_mul_f32_e32 v148, v31, v31
	v_pk_add_f32 v[148:149], v[152:153], v[148:149]
	v_fmamk_f32 v19, v201, 0xba800000, v19
	v_pk_add_f32 v[148:149], v[170:171], v[148:149]
	v_fmamk_f32 v18, v201, 0xba800000, v18
	v_pk_add_f32 v[154:155], v[154:155], v[154:155] op_sel_hi:[0,1]
	v_pk_add_f32 v[148:149], v[148:149], v[148:149] op_sel_hi:[0,1]
	v_mul_f32_e32 v154, v18, v18
	v_mul_f32_e32 v148, v19, v19
	v_pk_add_f32 v[148:149], v[154:155], v[148:149]
	v_fmamk_f32 v7, v201, 0xba800000, v7
	v_pk_add_f32 v[148:149], v[172:173], v[148:149]
	v_fmamk_f32 v6, v201, 0xba800000, v6
	v_pk_add_f32 v[156:157], v[156:157], v[156:157] op_sel_hi:[0,1]
	v_pk_add_f32 v[148:149], v[148:149], v[148:149] op_sel_hi:[0,1]
	v_mul_f32_e32 v156, v6, v6
	v_mul_f32_e32 v148, v7, v7
	v_pk_add_f32 v[148:149], v[156:157], v[148:149]
	ds_read_b128 v[182:185], v187
	ds_read_b128 v[162:165], v187 offset:128
	v_pk_add_f32 v[148:149], v[174:175], v[148:149]
	ds_read_b128 v[178:181], v187 offset:256
	ds_read_b128 v[158:161], v187 offset:384
	v_add_f32_e32 v128, v148, v149
	s_nop 1
	v_add_f32_dpp v128, v128, v128 quad_perm:[1,0,3,2] row_mask:0xf bank_mask:0xf bound_ctrl:1
	s_nop 1
	v_add_f32_dpp v128, v128, v128 quad_perm:[2,3,0,1] row_mask:0xf bank_mask:0xf bound_ctrl:1
	s_nop 1
	v_add_f32_dpp v128, v128, v128 row_half_mirror row_mask:0xf bank_mask:0xf bound_ctrl:1
	v_fmamk_f32 v128, v128, 0x3a800000, v186
	v_rsq_f32_e32 v128, v128
	s_nop 0
	v_pk_mul_f32 v[124:125], v[124:125], v[128:129] op_sel_hi:[1,0]
	v_pk_mul_f32 v[126:127], v[126:127], v[128:129] op_sel_hi:[1,0]
	v_pk_mul_f32 v[120:121], v[120:121], v[128:129] op_sel_hi:[1,0]
	v_pk_mul_f32 v[122:123], v[122:123], v[128:129] op_sel_hi:[1,0]
	v_pk_mul_f32 v[116:117], v[116:117], v[128:129] op_sel_hi:[1,0]
	v_pk_mul_f32 v[118:119], v[118:119], v[128:129] op_sel_hi:[1,0]
	v_pk_mul_f32 v[108:109], v[108:109], v[128:129] op_sel_hi:[1,0]
	v_pk_mul_f32 v[110:111], v[110:111], v[128:129] op_sel_hi:[1,0]
	v_pk_mul_f32 v[194:195], v[80:81], v[128:129] op_sel_hi:[1,0]
	v_pk_mul_f32 v[196:197], v[82:83], v[128:129] op_sel_hi:[1,0]
	v_pk_mul_f32 v[80:81], v[74:75], v[128:129] op_sel_hi:[1,0]
	v_pk_mul_f32 v[74:75], v[76:77], v[128:129] op_sel_hi:[1,0]
	v_pk_mul_f32 v[76:77], v[78:79], v[128:129] op_sel_hi:[1,0]
	v_pk_mul_f32 v[78:79], v[70:71], v[128:129] op_sel_hi:[1,0]
	v_pk_mul_f32 v[70:71], v[60:61], v[128:129] op_sel_hi:[1,0]
	v_pk_mul_f32 v[82:83], v[62:63], v[128:129] op_sel_hi:[1,0]
	v_pk_mul_f32 v[60:61], v[64:65], v[128:129] op_sel_hi:[1,0]
	v_pk_mul_f32 v[62:63], v[66:67], v[128:129] op_sel_hi:[1,0]
	v_pk_mul_f32 v[64:65], v[58:59], v[128:129] op_sel_hi:[1,0]
	v_pk_mul_f32 v[58:59], v[48:49], v[128:129] op_sel_hi:[1,0]
	v_pk_mul_f32 v[66:67], v[50:51], v[128:129] op_sel_hi:[1,0]
	v_pk_mul_f32 v[48:49], v[38:39], v[128:129] op_sel_hi:[1,0]
	v_pk_mul_f32 v[38:39], v[40:41], v[128:129] op_sel_hi:[1,0]
	v_pk_mul_f32 v[40:41], v[32:33], v[128:129] op_sel_hi:[1,0]
	v_pk_mul_f32 v[50:51], v[34:35], v[128:129] op_sel_hi:[1,0]
	v_pk_mul_f32 v[32:33], v[26:27], v[128:129] op_sel_hi:[1,0]
	v_pk_mul_f32 v[26:27], v[28:29], v[128:129] op_sel_hi:[1,0]
	v_pk_mul_f32 v[28:29], v[30:31], v[128:129] op_sel_hi:[1,0]
	v_pk_mul_f32 v[30:31], v[22:23], v[128:129] op_sel_hi:[1,0]
	v_pk_mul_f32 v[22:23], v[12:13], v[128:129] op_sel_hi:[1,0]
	v_pk_mul_f32 v[34:35], v[14:15], v[128:129] op_sel_hi:[1,0]
	v_pk_mul_f32 v[12:13], v[16:17], v[128:129] op_sel_hi:[1,0]
	v_pk_mul_f32 v[14:15], v[18:19], v[128:129] op_sel_hi:[1,0]
	v_pk_mul_f32 v[16:17], v[2:3], v[128:129] op_sel_hi:[1,0]
	v_pk_mul_f32 v[2:3], v[4:5], v[128:129] op_sel_hi:[1,0]
	v_pk_mul_f32 v[4:5], v[6:7], v[128:129] op_sel_hi:[1,0]
	s_waitcnt lgkmcnt(3)
	v_pk_fma_f32 v[6:7], v[132:133], v[126:127], v[184:185]
	v_pk_fma_f32 v[18:19], v[134:135], v[124:125], v[182:183]
	v_pk_mul_f32 v[156:157], v[96:97], v[128:129] op_sel_hi:[1,0]
	v_pk_mul_f32 v[166:167], v[98:99], v[128:129] op_sel_hi:[1,0]
	v_pk_mul_f32 v[172:173], v[92:93], v[128:129] op_sel_hi:[1,0]
	v_pk_mul_f32 v[174:175], v[94:95], v[128:129] op_sel_hi:[1,0]
	v_pk_mul_f32 v[176:177], v[84:85], v[128:129] op_sel_hi:[1,0]
	v_pk_mul_f32 v[188:189], v[86:87], v[128:129] op_sel_hi:[1,0]
	v_pk_mul_f32 v[190:191], v[88:89], v[128:129] op_sel_hi:[1,0]
	v_pk_mul_f32 v[192:193], v[90:91], v[128:129] op_sel_hi:[1,0]
	s_waitcnt lgkmcnt(2)
	v_pk_fma_f32 v[84:85], v[136:137], v[122:123], v[164:165]
	v_pk_fma_f32 v[86:87], v[138:139], v[120:121], v[162:163]
	s_waitcnt lgkmcnt(1)
	v_pk_fma_f32 v[88:89], v[140:141], v[118:119], v[180:181]
	v_pk_fma_f32 v[90:91], v[142:143], v[116:117], v[178:179]
	s_waitcnt lgkmcnt(0)
	v_pk_fma_f32 v[92:93], v[144:145], v[110:111], v[160:161]
	v_pk_fma_f32 v[94:95], v[146:147], v[108:109], v[158:159]
	v_bfe_u32 v96, v18, 16, 1
	v_bfe_u32 v98, v6, 16, 1
	v_pk_mul_f32 v[152:153], v[104:105], v[128:129] op_sel_hi:[1,0]
	v_pk_mul_f32 v[154:155], v[106:107], v[128:129] op_sel_hi:[1,0]
	v_pk_mul_f32 v[168:169], v[100:101], v[128:129] op_sel_hi:[1,0]
	v_pk_mul_f32 v[170:171], v[102:103], v[128:129] op_sel_hi:[1,0]
	v_bfe_u32 v97, v19, 16, 1
	v_bfe_u32 v99, v7, 16, 1
	v_bfe_u32 v100, v86, 16, 1
	v_bfe_u32 v102, v84, 16, 1
	v_bfe_u32 v104, v90, 16, 1
	v_bfe_u32 v106, v88, 16, 1
	v_bfe_u32 v108, v94, 16, 1
	v_bfe_u32 v110, v92, 16, 1
	v_add3_u32 v18, v18, v96, s5
	v_add3_u32 v6, v6, v98, s5
	v_bfe_u32 v101, v87, 16, 1
	v_bfe_u32 v103, v85, 16, 1
	v_bfe_u32 v105, v91, 16, 1
	v_bfe_u32 v107, v89, 16, 1
	v_bfe_u32 v109, v95, 16, 1
	v_bfe_u32 v111, v93, 16, 1
	v_add3_u32 v19, v19, v97, s5
	v_add3_u32 v7, v7, v99, s5
	v_add3_u32 v86, v86, v100, s5
	v_add3_u32 v84, v84, v102, s5
	v_add3_u32 v90, v90, v104, s5
	v_add3_u32 v88, v88, v106, s5
	v_add3_u32 v94, v94, v108, s5
	v_add3_u32 v92, v92, v110, s5
	v_lshrrev_b32_e32 v18, 16, v18
	v_lshrrev_b32_e32 v96, 16, v6
	v_add3_u32 v87, v87, v101, s5
	v_add3_u32 v85, v85, v103, s5
	v_add3_u32 v91, v91, v105, s5
	v_add3_u32 v89, v89, v107, s5
	v_add3_u32 v95, v95, v109, s5
	v_add3_u32 v93, v93, v111, s5
	v_lshrrev_b32_e32 v86, 16, v86
	v_lshrrev_b32_e32 v84, 16, v84
	v_lshrrev_b32_e32 v90, 16, v90
	v_lshrrev_b32_e32 v88, 16, v88
	v_lshrrev_b32_e32 v94, 16, v94
	v_lshrrev_b32_e32 v92, 16, v92
	v_and_or_b32 v6, v19, s6, v18
	v_and_or_b32 v7, v7, s6, v96
	v_and_or_b32 v18, v87, s6, v86
	v_and_or_b32 v19, v85, s6, v84
	v_and_or_b32 v84, v91, s6, v90
	v_and_or_b32 v85, v89, s6, v88
	v_and_or_b32 v86, v95, s6, v94
	v_and_or_b32 v87, v93, s6, v92
	global_store_dwordx2 v[130:131], v[6:7], off
	global_store_dwordx2 v[130:131], v[18:19], off offset:64
	global_store_dwordx2 v[130:131], v[84:85], off offset:128
	global_store_dwordx2 v[130:131], v[86:87], off offset:192
	v_pk_mul_f32 v[148:149], v[112:113], v[128:129] op_sel_hi:[1,0]
	v_pk_mul_f32 v[150:151], v[114:115], v[128:129] op_sel_hi:[1,0]
	ds_read_b128 v[84:87], v187 offset:4608
	ds_read_b128 v[88:91], v187 offset:4736
	ds_read_b128 v[92:95], v187 offset:512
	ds_read_b128 v[96:99], v187 offset:640
	ds_read_b128 v[100:103], v187 offset:4864
	ds_read_b128 v[104:107], v187 offset:4992
	ds_read_b128 v[108:111], v187 offset:768
	ds_read_b128 v[112:115], v187 offset:896
	s_waitcnt lgkmcnt(7)
	v_pk_add_f32 v[6:7], v[86:87], 1.0 op_sel_hi:[1,0]
	v_pk_add_f32 v[18:19], v[84:85], 1.0 op_sel_hi:[1,0]
	s_waitcnt lgkmcnt(6)
	v_pk_add_f32 v[84:85], v[90:91], 1.0 op_sel_hi:[1,0]
	v_pk_add_f32 v[86:87], v[88:89], 1.0 op_sel_hi:[1,0]
	s_waitcnt lgkmcnt(3)
	v_pk_add_f32 v[88:89], v[102:103], 1.0 op_sel_hi:[1,0]
	v_pk_add_f32 v[90:91], v[100:101], 1.0 op_sel_hi:[1,0]
	s_waitcnt lgkmcnt(2)
	v_pk_add_f32 v[100:101], v[106:107], 1.0 op_sel_hi:[1,0]
	v_pk_add_f32 v[102:103], v[104:105], 1.0 op_sel_hi:[1,0]
	v_pk_fma_f32 v[6:7], v[6:7], v[150:151], v[94:95]
	v_pk_fma_f32 v[18:19], v[18:19], v[148:149], v[92:93]
	v_pk_fma_f32 v[84:85], v[84:85], v[154:155], v[98:99]
	v_pk_fma_f32 v[86:87], v[86:87], v[152:153], v[96:97]
	s_waitcnt lgkmcnt(1)
	v_pk_fma_f32 v[88:89], v[88:89], v[166:167], v[110:111]
	v_pk_fma_f32 v[90:91], v[90:91], v[156:157], v[108:109]
	s_waitcnt lgkmcnt(0)
	v_pk_fma_f32 v[92:93], v[100:101], v[170:171], v[114:115]
	v_pk_fma_f32 v[94:95], v[102:103], v[168:169], v[112:113]
	v_bfe_u32 v96, v18, 16, 1
	v_bfe_u32 v98, v6, 16, 1
	v_bfe_u32 v97, v19, 16, 1
	v_bfe_u32 v99, v7, 16, 1
	v_bfe_u32 v100, v86, 16, 1
	v_bfe_u32 v102, v84, 16, 1
	v_bfe_u32 v104, v90, 16, 1
	v_bfe_u32 v106, v88, 16, 1
	v_bfe_u32 v108, v94, 16, 1
	v_bfe_u32 v110, v92, 16, 1
	v_add3_u32 v18, v18, v96, s5
	v_add3_u32 v6, v6, v98, s5
	v_bfe_u32 v101, v87, 16, 1
	v_bfe_u32 v103, v85, 16, 1
	v_bfe_u32 v105, v91, 16, 1
	v_bfe_u32 v107, v89, 16, 1
	v_bfe_u32 v109, v95, 16, 1
	v_bfe_u32 v111, v93, 16, 1
	v_add3_u32 v19, v19, v97, s5
	v_add3_u32 v7, v7, v99, s5
	v_add3_u32 v86, v86, v100, s5
	v_add3_u32 v84, v84, v102, s5
	v_add3_u32 v90, v90, v104, s5
	v_add3_u32 v88, v88, v106, s5
	v_add3_u32 v94, v94, v108, s5
	v_add3_u32 v92, v92, v110, s5
	v_lshrrev_b32_e32 v18, 16, v18
	v_lshrrev_b32_e32 v96, 16, v6
	v_add3_u32 v87, v87, v101, s5
	v_add3_u32 v85, v85, v103, s5
	v_add3_u32 v91, v91, v105, s5
	v_add3_u32 v89, v89, v107, s5
	v_add3_u32 v95, v95, v109, s5
	v_add3_u32 v93, v93, v111, s5
	v_lshrrev_b32_e32 v86, 16, v86
	v_lshrrev_b32_e32 v84, 16, v84
	v_lshrrev_b32_e32 v90, 16, v90
	v_lshrrev_b32_e32 v88, 16, v88
	v_lshrrev_b32_e32 v94, 16, v94
	v_lshrrev_b32_e32 v92, 16, v92
	v_and_or_b32 v6, v19, s6, v18
	v_and_or_b32 v7, v7, s6, v96
	v_and_or_b32 v18, v87, s6, v86
	v_and_or_b32 v19, v85, s6, v84
	v_and_or_b32 v84, v91, s6, v90
	v_and_or_b32 v85, v89, s6, v88
	v_and_or_b32 v86, v95, s6, v94
	v_and_or_b32 v87, v93, s6, v92
	global_store_dwordx2 v[130:131], v[6:7], off offset:256
	global_store_dwordx2 v[130:131], v[18:19], off offset:320
	global_store_dwordx2 v[130:131], v[84:85], off offset:384
	global_store_dwordx2 v[130:131], v[86:87], off offset:448
	ds_read_b128 v[84:87], v187 offset:5120
	ds_read_b128 v[88:91], v187 offset:5248
	ds_read_b128 v[92:95], v187 offset:1024
	ds_read_b128 v[96:99], v187 offset:1152
	ds_read_b128 v[100:103], v187 offset:5376
	ds_read_b128 v[104:107], v187 offset:5504
	ds_read_b128 v[108:111], v187 offset:1280
	ds_read_b128 v[112:115], v187 offset:1408
	s_waitcnt lgkmcnt(7)
	v_pk_add_f32 v[6:7], v[86:87], 1.0 op_sel_hi:[1,0]
	v_pk_add_f32 v[18:19], v[84:85], 1.0 op_sel_hi:[1,0]
	s_waitcnt lgkmcnt(6)
	v_pk_add_f32 v[84:85], v[90:91], 1.0 op_sel_hi:[1,0]
	v_pk_add_f32 v[86:87], v[88:89], 1.0 op_sel_hi:[1,0]
	s_waitcnt lgkmcnt(3)
	v_pk_add_f32 v[88:89], v[102:103], 1.0 op_sel_hi:[1,0]
	v_pk_add_f32 v[90:91], v[100:101], 1.0 op_sel_hi:[1,0]
	s_waitcnt lgkmcnt(2)
	v_pk_add_f32 v[100:101], v[106:107], 1.0 op_sel_hi:[1,0]
	v_pk_add_f32 v[102:103], v[104:105], 1.0 op_sel_hi:[1,0]
	v_pk_fma_f32 v[6:7], v[6:7], v[174:175], v[94:95]
	v_pk_fma_f32 v[18:19], v[18:19], v[172:173], v[92:93]
	v_pk_fma_f32 v[84:85], v[84:85], v[188:189], v[98:99]
	v_pk_fma_f32 v[86:87], v[86:87], v[176:177], v[96:97]
	s_waitcnt lgkmcnt(1)
	v_pk_fma_f32 v[88:89], v[88:89], v[192:193], v[110:111]
	v_pk_fma_f32 v[90:91], v[90:91], v[190:191], v[108:109]
	s_waitcnt lgkmcnt(0)
	v_pk_fma_f32 v[92:93], v[100:101], v[196:197], v[114:115]
	v_pk_fma_f32 v[94:95], v[102:103], v[194:195], v[112:113]
	v_bfe_u32 v96, v18, 16, 1
	v_bfe_u32 v98, v6, 16, 1
	v_bfe_u32 v97, v19, 16, 1
	v_bfe_u32 v99, v7, 16, 1
	v_bfe_u32 v100, v86, 16, 1
	v_bfe_u32 v102, v84, 16, 1
	v_bfe_u32 v104, v90, 16, 1
	v_bfe_u32 v106, v88, 16, 1
	v_bfe_u32 v108, v94, 16, 1
	v_bfe_u32 v110, v92, 16, 1
	v_add3_u32 v18, v18, v96, s5
	v_add3_u32 v6, v6, v98, s5
	v_bfe_u32 v101, v87, 16, 1
	v_bfe_u32 v103, v85, 16, 1
	v_bfe_u32 v105, v91, 16, 1
	v_bfe_u32 v107, v89, 16, 1
	v_bfe_u32 v109, v95, 16, 1
	v_bfe_u32 v111, v93, 16, 1
	v_add3_u32 v19, v19, v97, s5
	v_add3_u32 v7, v7, v99, s5
	v_add3_u32 v86, v86, v100, s5
	v_add3_u32 v84, v84, v102, s5
	v_add3_u32 v90, v90, v104, s5
	v_add3_u32 v88, v88, v106, s5
	v_add3_u32 v94, v94, v108, s5
	v_add3_u32 v92, v92, v110, s5
	v_lshrrev_b32_e32 v18, 16, v18
	v_lshrrev_b32_e32 v96, 16, v6
	v_add3_u32 v87, v87, v101, s5
	v_add3_u32 v85, v85, v103, s5
	v_add3_u32 v91, v91, v105, s5
	v_add3_u32 v89, v89, v107, s5
	v_add3_u32 v95, v95, v109, s5
	v_add3_u32 v93, v93, v111, s5
	v_lshrrev_b32_e32 v86, 16, v86
	v_lshrrev_b32_e32 v84, 16, v84
	v_lshrrev_b32_e32 v90, 16, v90
	v_lshrrev_b32_e32 v88, 16, v88
	v_lshrrev_b32_e32 v94, 16, v94
	v_lshrrev_b32_e32 v92, 16, v92
	v_and_or_b32 v6, v19, s6, v18
	v_and_or_b32 v7, v7, s6, v96
	v_and_or_b32 v18, v87, s6, v86
	v_and_or_b32 v19, v85, s6, v84
	v_and_or_b32 v84, v91, s6, v90
	v_and_or_b32 v85, v89, s6, v88
	v_and_or_b32 v86, v95, s6, v94
	v_and_or_b32 v87, v93, s6, v92
	global_store_dwordx2 v[130:131], v[6:7], off offset:512
	global_store_dwordx2 v[130:131], v[18:19], off offset:576
	global_store_dwordx2 v[130:131], v[84:85], off offset:640
	global_store_dwordx2 v[130:131], v[86:87], off offset:704
	ds_read_b128 v[84:87], v187 offset:5632
	ds_read_b128 v[88:91], v187 offset:5760
	ds_read_b128 v[92:95], v187 offset:1536
	ds_read_b128 v[96:99], v187 offset:1664
	ds_read_b128 v[100:103], v187 offset:5888
	ds_read_b128 v[104:107], v187 offset:6016
	ds_read_b128 v[108:111], v187 offset:1792
	ds_read_b128 v[112:115], v187 offset:1920
	v_pk_mul_f32 v[72:73], v[72:73], v[128:129] op_sel_hi:[1,0]
	s_waitcnt lgkmcnt(7)
	v_pk_add_f32 v[6:7], v[86:87], 1.0 op_sel_hi:[1,0]
	v_pk_add_f32 v[18:19], v[84:85], 1.0 op_sel_hi:[1,0]
	v_pk_mul_f32 v[68:69], v[68:69], v[128:129] op_sel_hi:[1,0]
	s_waitcnt lgkmcnt(6)
	v_pk_add_f32 v[84:85], v[90:91], 1.0 op_sel_hi:[1,0]
	v_pk_add_f32 v[86:87], v[88:89], 1.0 op_sel_hi:[1,0]
	s_waitcnt lgkmcnt(3)
	v_pk_add_f32 v[88:89], v[102:103], 1.0 op_sel_hi:[1,0]
	v_pk_add_f32 v[90:91], v[100:101], 1.0 op_sel_hi:[1,0]
	s_waitcnt lgkmcnt(2)
	v_pk_add_f32 v[100:101], v[106:107], 1.0 op_sel_hi:[1,0]
	v_pk_add_f32 v[102:103], v[104:105], 1.0 op_sel_hi:[1,0]
	v_pk_fma_f32 v[6:7], v[6:7], v[80:81], v[94:95]
	v_pk_fma_f32 v[18:19], v[18:19], v[72:73], v[92:93]
	v_pk_fma_f32 v[72:73], v[84:85], v[76:77], v[98:99]
	v_pk_fma_f32 v[74:75], v[86:87], v[74:75], v[96:97]
	s_waitcnt lgkmcnt(1)
	v_pk_fma_f32 v[76:77], v[88:89], v[78:79], v[110:111]
	v_pk_fma_f32 v[68:69], v[90:91], v[68:69], v[108:109]
	s_waitcnt lgkmcnt(0)
	v_pk_fma_f32 v[78:79], v[82:83], v[100:101], v[114:115]
	v_pk_fma_f32 v[70:71], v[70:71], v[102:103], v[112:113]
	v_bfe_u32 v80, v18, 16, 1
	v_bfe_u32 v82, v6, 16, 1
	v_bfe_u32 v81, v19, 16, 1
	v_bfe_u32 v83, v7, 16, 1
	v_bfe_u32 v84, v74, 16, 1
	v_bfe_u32 v86, v72, 16, 1
	v_bfe_u32 v88, v68, 16, 1
	v_bfe_u32 v90, v76, 16, 1
	v_bfe_u32 v92, v70, 16, 1
	v_bfe_u32 v94, v78, 16, 1
	v_add3_u32 v18, v18, v80, s5
	v_add3_u32 v6, v6, v82, s5
	v_bfe_u32 v85, v75, 16, 1
	v_bfe_u32 v87, v73, 16, 1
	v_bfe_u32 v89, v69, 16, 1
	v_bfe_u32 v91, v77, 16, 1
	v_bfe_u32 v93, v71, 16, 1
	v_bfe_u32 v95, v79, 16, 1
	v_add3_u32 v19, v19, v81, s5
	v_add3_u32 v7, v7, v83, s5
	v_add3_u32 v74, v74, v84, s5
	v_add3_u32 v72, v72, v86, s5
	v_add3_u32 v68, v68, v88, s5
	v_add3_u32 v76, v76, v90, s5
	v_add3_u32 v70, v70, v92, s5
	v_add3_u32 v78, v78, v94, s5
	v_lshrrev_b32_e32 v18, 16, v18
	v_lshrrev_b32_e32 v80, 16, v6
	v_add3_u32 v75, v75, v85, s5
	v_add3_u32 v73, v73, v87, s5
	v_add3_u32 v69, v69, v89, s5
	v_add3_u32 v77, v77, v91, s5
	v_add3_u32 v71, v71, v93, s5
	v_add3_u32 v79, v79, v95, s5
	v_lshrrev_b32_e32 v74, 16, v74
	v_lshrrev_b32_e32 v72, 16, v72
	v_lshrrev_b32_e32 v68, 16, v68
	v_lshrrev_b32_e32 v76, 16, v76
	v_lshrrev_b32_e32 v70, 16, v70
	v_lshrrev_b32_e32 v78, 16, v78
	v_and_or_b32 v6, v19, s6, v18
	v_and_or_b32 v7, v7, s6, v80
	v_and_or_b32 v18, v75, s6, v74
	v_and_or_b32 v19, v73, s6, v72
	v_and_or_b32 v68, v69, s6, v68
	v_and_or_b32 v69, v77, s6, v76
	v_and_or_b32 v70, v71, s6, v70
	v_and_or_b32 v71, v79, s6, v78
	global_store_dwordx2 v[130:131], v[6:7], off offset:768
	global_store_dwordx2 v[130:131], v[18:19], off offset:832
	global_store_dwordx2 v[130:131], v[68:69], off offset:896
	global_store_dwordx2 v[130:131], v[70:71], off offset:960
	ds_read_b128 v[68:71], v187 offset:6144
	ds_read_b128 v[72:75], v187 offset:6272
	ds_read_b128 v[76:79], v187 offset:2048
	ds_read_b128 v[80:83], v187 offset:2176
	ds_read_b128 v[84:87], v187 offset:6400
	ds_read_b128 v[88:91], v187 offset:6528
	ds_read_b128 v[92:95], v187 offset:2304
	ds_read_b128 v[96:99], v187 offset:2432
	s_waitcnt lgkmcnt(7)
	v_pk_add_f32 v[6:7], v[70:71], 1.0 op_sel_hi:[1,0]
	v_pk_add_f32 v[18:19], v[68:69], 1.0 op_sel_hi:[1,0]
	v_pk_mul_f32 v[56:57], v[56:57], v[128:129] op_sel_hi:[1,0]
	v_pk_mul_f32 v[52:53], v[52:53], v[128:129] op_sel_hi:[1,0]
	v_pk_mul_f32 v[54:55], v[54:55], v[128:129] op_sel_hi:[1,0]
	s_waitcnt lgkmcnt(6)
	v_pk_add_f32 v[68:69], v[74:75], 1.0 op_sel_hi:[1,0]
	v_pk_add_f32 v[70:71], v[72:73], 1.0 op_sel_hi:[1,0]
	s_waitcnt lgkmcnt(3)
	v_pk_add_f32 v[72:73], v[86:87], 1.0 op_sel_hi:[1,0]
	v_pk_add_f32 v[74:75], v[84:85], 1.0 op_sel_hi:[1,0]
	s_waitcnt lgkmcnt(2)
	v_pk_add_f32 v[84:85], v[90:91], 1.0 op_sel_hi:[1,0]
	v_pk_add_f32 v[86:87], v[88:89], 1.0 op_sel_hi:[1,0]
	v_pk_fma_f32 v[6:7], v[62:63], v[6:7], v[78:79]
	v_pk_fma_f32 v[18:19], v[60:61], v[18:19], v[76:77]
	v_pk_fma_f32 v[60:61], v[64:65], v[68:69], v[82:83]
	v_pk_fma_f32 v[56:57], v[56:57], v[70:71], v[80:81]
	s_waitcnt lgkmcnt(1)
	v_pk_fma_f32 v[62:63], v[66:67], v[72:73], v[94:95]
	v_pk_fma_f32 v[58:59], v[58:59], v[74:75], v[92:93]
	s_waitcnt lgkmcnt(0)
	v_pk_fma_f32 v[54:55], v[54:55], v[84:85], v[98:99]
	v_pk_fma_f32 v[52:53], v[52:53], v[86:87], v[96:97]
	v_bfe_u32 v64, v18, 16, 1
	v_bfe_u32 v66, v6, 16, 1
	v_bfe_u32 v65, v19, 16, 1
	v_bfe_u32 v67, v7, 16, 1
	v_bfe_u32 v68, v56, 16, 1
	v_bfe_u32 v70, v60, 16, 1
	v_bfe_u32 v72, v58, 16, 1
	v_bfe_u32 v74, v62, 16, 1
	v_bfe_u32 v76, v52, 16, 1
	v_bfe_u32 v77, v53, 16, 1
	v_bfe_u32 v78, v54, 16, 1
	v_add3_u32 v18, v18, v64, s5
	v_add3_u32 v6, v6, v66, s5
	v_bfe_u32 v69, v57, 16, 1
	v_bfe_u32 v71, v61, 16, 1
	v_bfe_u32 v73, v59, 16, 1
	v_bfe_u32 v75, v63, 16, 1
	v_bfe_u32 v79, v55, 16, 1
	v_add3_u32 v19, v19, v65, s5
	v_add3_u32 v7, v7, v67, s5
	v_add3_u32 v56, v56, v68, s5
	v_add3_u32 v60, v60, v70, s5
	v_add3_u32 v58, v58, v72, s5
	v_add3_u32 v62, v62, v74, s5
	v_add3_u32 v52, v52, v76, s5
	v_add3_u32 v64, v53, v77, s5
	v_add3_u32 v53, v54, v78, s5
	v_lshrrev_b32_e32 v18, 16, v18
	v_lshrrev_b32_e32 v54, 16, v6
	v_add3_u32 v57, v57, v69, s5
	v_add3_u32 v61, v61, v71, s5
	v_add3_u32 v59, v59, v73, s5
	v_add3_u32 v63, v63, v75, s5
	v_add3_u32 v55, v55, v79, s5
	v_lshrrev_b32_e32 v56, 16, v56
	v_lshrrev_b32_e32 v60, 16, v60
	v_lshrrev_b32_e32 v58, 16, v58
	v_lshrrev_b32_e32 v62, 16, v62
	v_lshrrev_b32_e32 v65, 16, v52
	v_lshrrev_b32_e32 v66, 16, v53
	v_and_or_b32 v6, v19, s6, v18
	v_and_or_b32 v7, v7, s6, v54
	v_and_or_b32 v18, v57, s6, v56
	v_and_or_b32 v19, v61, s6, v60
	v_and_or_b32 v52, v59, s6, v58
	v_and_or_b32 v53, v63, s6, v62
	v_and_or_b32 v54, v64, s6, v65
	v_and_or_b32 v55, v55, s6, v66
	global_store_dwordx2 v[130:131], v[6:7], off offset:1024
	global_store_dwordx2 v[130:131], v[18:19], off offset:1088
	global_store_dwordx2 v[130:131], v[52:53], off offset:1152
	global_store_dwordx2 v[130:131], v[54:55], off offset:1216
	ds_read_b128 v[52:55], v187 offset:6656
	ds_read_b128 v[56:59], v187 offset:6784
	ds_read_b128 v[60:63], v187 offset:2560
	ds_read_b128 v[64:67], v187 offset:2688
	ds_read_b128 v[68:71], v187 offset:6912
	ds_read_b128 v[72:75], v187 offset:7040
	ds_read_b128 v[76:79], v187 offset:2816
	ds_read_b128 v[80:83], v187 offset:2944
	v_pk_mul_f32 v[44:45], v[44:45], v[128:129] op_sel_hi:[1,0]
	v_pk_mul_f32 v[46:47], v[46:47], v[128:129] op_sel_hi:[1,0]
	s_waitcnt lgkmcnt(7)
	v_pk_add_f32 v[6:7], v[54:55], 1.0 op_sel_hi:[1,0]
	v_pk_add_f32 v[18:19], v[52:53], 1.0 op_sel_hi:[1,0]
	v_pk_mul_f32 v[36:37], v[36:37], v[128:129] op_sel_hi:[1,0]
	v_pk_mul_f32 v[42:43], v[42:43], v[128:129] op_sel_hi:[1,0]
	s_waitcnt lgkmcnt(6)
	v_pk_add_f32 v[52:53], v[58:59], 1.0 op_sel_hi:[1,0]
	v_pk_add_f32 v[54:55], v[56:57], 1.0 op_sel_hi:[1,0]
	s_waitcnt lgkmcnt(3)
	v_pk_add_f32 v[56:57], v[70:71], 1.0 op_sel_hi:[1,0]
	v_pk_add_f32 v[58:59], v[68:69], 1.0 op_sel_hi:[1,0]
	s_waitcnt lgkmcnt(2)
	v_pk_add_f32 v[68:69], v[74:75], 1.0 op_sel_hi:[1,0]
	v_pk_add_f32 v[70:71], v[72:73], 1.0 op_sel_hi:[1,0]
	v_pk_fma_f32 v[6:7], v[46:47], v[6:7], v[62:63]
	v_pk_fma_f32 v[18:19], v[44:45], v[18:19], v[60:61]
	v_pk_fma_f32 v[44:45], v[48:49], v[52:53], v[66:67]
	v_pk_fma_f32 v[36:37], v[36:37], v[54:55], v[64:65]
	s_waitcnt lgkmcnt(1)
	v_pk_fma_f32 v[42:43], v[42:43], v[56:57], v[78:79]
	v_pk_fma_f32 v[38:39], v[38:39], v[58:59], v[76:77]
	s_waitcnt lgkmcnt(0)
	v_pk_fma_f32 v[46:47], v[50:51], v[68:69], v[82:83]
	v_pk_fma_f32 v[40:41], v[40:41], v[70:71], v[80:81]
	v_bfe_u32 v48, v18, 16, 1
	v_bfe_u32 v50, v6, 16, 1
	v_bfe_u32 v49, v19, 16, 1
	v_bfe_u32 v51, v7, 16, 1
	v_bfe_u32 v52, v36, 16, 1
	v_bfe_u32 v54, v44, 16, 1
	v_bfe_u32 v56, v38, 16, 1
	v_bfe_u32 v58, v42, 16, 1
	v_bfe_u32 v60, v40, 16, 1
	v_bfe_u32 v62, v46, 16, 1
	v_add3_u32 v18, v18, v48, s5
	v_add3_u32 v6, v6, v50, s5
	v_bfe_u32 v53, v37, 16, 1
	v_bfe_u32 v55, v45, 16, 1
	v_bfe_u32 v57, v39, 16, 1
	v_bfe_u32 v59, v43, 16, 1
	v_bfe_u32 v61, v41, 16, 1
	v_bfe_u32 v63, v47, 16, 1
	v_add3_u32 v19, v19, v49, s5
	v_add3_u32 v7, v7, v51, s5
	v_add3_u32 v36, v36, v52, s5
	v_add3_u32 v44, v44, v54, s5
	v_add3_u32 v38, v38, v56, s5
	v_add3_u32 v42, v42, v58, s5
	v_add3_u32 v40, v40, v60, s5
	v_add3_u32 v46, v46, v62, s5
	v_lshrrev_b32_e32 v18, 16, v18
	v_lshrrev_b32_e32 v48, 16, v6
	v_add3_u32 v37, v37, v53, s5
	v_add3_u32 v45, v45, v55, s5
	v_add3_u32 v39, v39, v57, s5
	v_add3_u32 v43, v43, v59, s5
	v_add3_u32 v41, v41, v61, s5
	v_add3_u32 v47, v47, v63, s5
	v_lshrrev_b32_e32 v36, 16, v36
	v_lshrrev_b32_e32 v44, 16, v44
	v_lshrrev_b32_e32 v38, 16, v38
	v_lshrrev_b32_e32 v42, 16, v42
	v_lshrrev_b32_e32 v40, 16, v40
	v_lshrrev_b32_e32 v46, 16, v46
	v_and_or_b32 v6, v19, s6, v18
	v_and_or_b32 v7, v7, s6, v48
	v_and_or_b32 v18, v37, s6, v36
	v_and_or_b32 v19, v45, s6, v44
	v_and_or_b32 v36, v39, s6, v38
	v_and_or_b32 v37, v43, s6, v42
	v_and_or_b32 v38, v41, s6, v40
	v_and_or_b32 v39, v47, s6, v46
	global_store_dwordx2 v[130:131], v[6:7], off offset:1280
	global_store_dwordx2 v[130:131], v[18:19], off offset:1344
	global_store_dwordx2 v[130:131], v[36:37], off offset:1408
	global_store_dwordx2 v[130:131], v[38:39], off offset:1472
	ds_read_b128 v[36:39], v187 offset:7168
	ds_read_b128 v[40:43], v187 offset:7296
	ds_read_b128 v[44:47], v187 offset:3072
	ds_read_b128 v[48:51], v187 offset:3200
	ds_read_b128 v[52:55], v187 offset:7424
	ds_read_b128 v[56:59], v187 offset:7552
	ds_read_b128 v[60:63], v187 offset:3328
	ds_read_b128 v[64:67], v187 offset:3456
	v_pk_mul_f32 v[24:25], v[24:25], v[128:129] op_sel_hi:[1,0]
	s_waitcnt lgkmcnt(7)
	v_pk_add_f32 v[6:7], v[38:39], 1.0 op_sel_hi:[1,0]
	v_pk_add_f32 v[18:19], v[36:37], 1.0 op_sel_hi:[1,0]
	v_pk_mul_f32 v[20:21], v[20:21], v[128:129] op_sel_hi:[1,0]
	s_waitcnt lgkmcnt(6)
	v_pk_add_f32 v[36:37], v[42:43], 1.0 op_sel_hi:[1,0]
	v_pk_add_f32 v[38:39], v[40:41], 1.0 op_sel_hi:[1,0]
	s_waitcnt lgkmcnt(3)
	v_pk_add_f32 v[40:41], v[54:55], 1.0 op_sel_hi:[1,0]
	v_pk_add_f32 v[42:43], v[52:53], 1.0 op_sel_hi:[1,0]
	s_waitcnt lgkmcnt(2)
	v_pk_add_f32 v[52:53], v[58:59], 1.0 op_sel_hi:[1,0]
	v_pk_add_f32 v[54:55], v[56:57], 1.0 op_sel_hi:[1,0]
	v_pk_fma_f32 v[6:7], v[32:33], v[6:7], v[46:47]
	v_pk_fma_f32 v[18:19], v[24:25], v[18:19], v[44:45]
	v_pk_fma_f32 v[24:25], v[28:29], v[36:37], v[50:51]
	v_pk_fma_f32 v[26:27], v[26:27], v[38:39], v[48:49]
	s_waitcnt lgkmcnt(1)
	v_pk_fma_f32 v[28:29], v[30:31], v[40:41], v[62:63]
	v_pk_fma_f32 v[20:21], v[20:21], v[42:43], v[60:61]
	s_waitcnt lgkmcnt(0)
	v_pk_fma_f32 v[30:31], v[34:35], v[52:53], v[66:67]
	v_pk_fma_f32 v[22:23], v[22:23], v[54:55], v[64:65]
	v_bfe_u32 v32, v18, 16, 1
	v_bfe_u32 v34, v6, 16, 1
	v_bfe_u32 v33, v19, 16, 1
	v_bfe_u32 v35, v7, 16, 1
	v_bfe_u32 v36, v26, 16, 1
	v_bfe_u32 v38, v24, 16, 1
	v_bfe_u32 v40, v20, 16, 1
	v_bfe_u32 v42, v28, 16, 1
	v_bfe_u32 v44, v22, 16, 1
	v_bfe_u32 v46, v30, 16, 1
	v_add3_u32 v18, v18, v32, s5
	v_add3_u32 v6, v6, v34, s5
	v_bfe_u32 v37, v27, 16, 1
	v_bfe_u32 v39, v25, 16, 1
	v_bfe_u32 v41, v21, 16, 1
	v_bfe_u32 v43, v29, 16, 1
	v_bfe_u32 v45, v23, 16, 1
	v_bfe_u32 v47, v31, 16, 1
	v_add3_u32 v19, v19, v33, s5
	v_add3_u32 v7, v7, v35, s5
	v_add3_u32 v26, v26, v36, s5
	v_add3_u32 v24, v24, v38, s5
	v_add3_u32 v20, v20, v40, s5
	v_add3_u32 v28, v28, v42, s5
	v_add3_u32 v22, v22, v44, s5
	v_add3_u32 v30, v30, v46, s5
	v_lshrrev_b32_e32 v18, 16, v18
	v_lshrrev_b32_e32 v32, 16, v6
	v_add3_u32 v27, v27, v37, s5
	v_add3_u32 v25, v25, v39, s5
	v_add3_u32 v21, v21, v41, s5
	v_add3_u32 v29, v29, v43, s5
	v_add3_u32 v23, v23, v45, s5
	v_add3_u32 v31, v31, v47, s5
	v_lshrrev_b32_e32 v26, 16, v26
	v_lshrrev_b32_e32 v24, 16, v24
	v_lshrrev_b32_e32 v20, 16, v20
	v_lshrrev_b32_e32 v28, 16, v28
	v_lshrrev_b32_e32 v22, 16, v22
	v_lshrrev_b32_e32 v30, 16, v30
	v_and_or_b32 v6, v19, s6, v18
	v_and_or_b32 v7, v7, s6, v32
	v_and_or_b32 v18, v27, s6, v26
	v_and_or_b32 v19, v25, s6, v24
	v_and_or_b32 v20, v21, s6, v20
	v_and_or_b32 v21, v29, s6, v28
	v_and_or_b32 v22, v23, s6, v22
	v_and_or_b32 v23, v31, s6, v30
	global_store_dwordx2 v[130:131], v[6:7], off offset:1536
	global_store_dwordx2 v[130:131], v[18:19], off offset:1600
	global_store_dwordx2 v[130:131], v[20:21], off offset:1664
	global_store_dwordx2 v[130:131], v[22:23], off offset:1728
	ds_read_b128 v[18:21], v187 offset:7680
	ds_read_b128 v[22:25], v187 offset:7808
	ds_read_b128 v[26:29], v187 offset:3584
	ds_read_b128 v[30:33], v187 offset:3712
	ds_read_b128 v[34:37], v187 offset:7936
	ds_read_b128 v[38:41], v187 offset:8064
	ds_read_b128 v[42:45], v187 offset:3840
	ds_read_b128 v[46:49], v187 offset:3968
	s_waitcnt lgkmcnt(7)
	v_pk_add_f32 v[6:7], v[20:21], 1.0 op_sel_hi:[1,0]
	v_pk_add_f32 v[18:19], v[18:19], 1.0 op_sel_hi:[1,0]
	v_pk_mul_f32 v[8:9], v[8:9], v[128:129] op_sel_hi:[1,0]
	v_pk_mul_f32 v[10:11], v[10:11], v[128:129] op_sel_hi:[1,0]
	v_pk_mul_f32 v[0:1], v[0:1], v[128:129] op_sel_hi:[1,0]
	s_waitcnt lgkmcnt(6)
	v_pk_add_f32 v[20:21], v[24:25], 1.0 op_sel_hi:[1,0]
	v_pk_add_f32 v[22:23], v[22:23], 1.0 op_sel_hi:[1,0]
	s_waitcnt lgkmcnt(3)
	v_pk_add_f32 v[24:25], v[36:37], 1.0 op_sel_hi:[1,0]
	v_pk_add_f32 v[34:35], v[34:35], 1.0 op_sel_hi:[1,0]
	s_waitcnt lgkmcnt(2)
	v_pk_add_f32 v[36:37], v[40:41], 1.0 op_sel_hi:[1,0]
	v_pk_add_f32 v[38:39], v[38:39], 1.0 op_sel_hi:[1,0]
	v_pk_fma_f32 v[6:7], v[14:15], v[6:7], v[28:29]
	v_pk_fma_f32 v[12:13], v[12:13], v[18:19], v[26:27]
	v_pk_fma_f32 v[10:11], v[10:11], v[20:21], v[32:33]
	v_pk_fma_f32 v[8:9], v[8:9], v[22:23], v[30:31]
	s_waitcnt lgkmcnt(1)
	v_pk_fma_f32 v[14:15], v[16:17], v[24:25], v[44:45]
	v_pk_fma_f32 v[0:1], v[0:1], v[34:35], v[42:43]
	s_waitcnt lgkmcnt(0)
	v_pk_fma_f32 v[4:5], v[4:5], v[36:37], v[48:49]
	v_pk_fma_f32 v[2:3], v[2:3], v[38:39], v[46:47]
	v_bfe_u32 v16, v12, 16, 1
	v_bfe_u32 v18, v6, 16, 1
	v_bfe_u32 v17, v13, 16, 1
	v_bfe_u32 v19, v7, 16, 1
	v_bfe_u32 v20, v8, 16, 1
	v_bfe_u32 v22, v10, 16, 1
	v_bfe_u32 v24, v0, 16, 1
	v_bfe_u32 v25, v1, 16, 1
	v_bfe_u32 v26, v14, 16, 1
	v_bfe_u32 v27, v15, 16, 1
	v_bfe_u32 v28, v2, 16, 1
	v_bfe_u32 v29, v3, 16, 1
	v_bfe_u32 v30, v4, 16, 1
	v_bfe_u32 v31, v5, 16, 1
	v_add3_u32 v12, v12, v16, s5
	v_add3_u32 v6, v6, v18, s5
	v_bfe_u32 v21, v9, 16, 1
	v_bfe_u32 v23, v11, 16, 1
	v_add3_u32 v13, v13, v17, s5
	v_add3_u32 v7, v7, v19, s5
	v_add3_u32 v8, v8, v20, s5
	v_add3_u32 v10, v10, v22, s5
	v_add3_u32 v0, v0, v24, s5
	v_add3_u32 v16, v1, v25, s5
	v_add3_u32 v1, v14, v26, s5
	v_add3_u32 v14, v15, v27, s5
	v_add3_u32 v2, v2, v28, s5
	v_add3_u32 v15, v3, v29, s5
	v_add3_u32 v3, v4, v30, s5
	v_add3_u32 v17, v5, v31, s5
	v_lshrrev_b32_e32 v4, 16, v12
	v_lshrrev_b32_e32 v5, 16, v6
	v_add3_u32 v9, v9, v21, s5
	v_add3_u32 v11, v11, v23, s5
	v_lshrrev_b32_e32 v6, 16, v8
	v_lshrrev_b32_e32 v8, 16, v10
	v_lshrrev_b32_e32 v10, 16, v0
	v_lshrrev_b32_e32 v12, 16, v1
	v_lshrrev_b32_e32 v18, 16, v2
	v_lshrrev_b32_e32 v19, 16, v3
	v_and_or_b32 v0, v13, s6, v4
	v_and_or_b32 v1, v7, s6, v5
	v_and_or_b32 v2, v9, s6, v6
	v_and_or_b32 v3, v11, s6, v8
	v_and_or_b32 v4, v16, s6, v10
	v_and_or_b32 v5, v14, s6, v12
	v_and_or_b32 v6, v15, s6, v18
	v_and_or_b32 v7, v17, s6, v19
	global_store_dwordx2 v[130:131], v[0:1], off offset:1792
	global_store_dwordx2 v[130:131], v[2:3], off offset:1856
	global_store_dwordx2 v[130:131], v[4:5], off offset:1920
	global_store_dwordx2 v[130:131], v[6:7], off offset:1984
	s_cbranch_scc0 .LBB0_189

	.amdhsa_kernel _Z10fwd_kernel4Args
		.amdhsa_group_segment_fixed_size 0
		.amdhsa_private_segment_fixed_size 0
		.amdhsa_kernarg_size 592
		.amdhsa_user_sgpr_count 2
		.amdhsa_user_sgpr_dispatch_ptr 0
		.amdhsa_user_sgpr_queue_ptr 0
		.amdhsa_user_sgpr_kernarg_segment_ptr 1
		.amdhsa_user_sgpr_dispatch_id 0
		.amdhsa_user_sgpr_kernarg_preload_length 0
		.amdhsa_user_sgpr_kernarg_preload_offset 0
		.amdhsa_user_sgpr_private_segment_size 0
		.amdhsa_uses_dynamic_stack 0
		.amdhsa_enable_private_segment 0
		.amdhsa_system_sgpr_workgroup_id_x 1
		.amdhsa_system_sgpr_workgroup_id_y 0
		.amdhsa_system_sgpr_workgroup_id_z 0
		.amdhsa_system_sgpr_workgroup_info 0
		.amdhsa_system_vgpr_workitem_id 0
		.amdhsa_next_free_vgpr 256
		.amdhsa_next_free_sgpr 99
		.amdhsa_accum_offset 256
		.amdhsa_reserve_vcc 1
		.amdhsa_float_round_mode_32 0
		.amdhsa_float_round_mode_16_64 0
		.amdhsa_float_denorm_mode_32 3
		.amdhsa_float_denorm_mode_16_64 3
		.amdhsa_dx10_clamp 1
		.amdhsa_ieee_mode 1
		.amdhsa_fp16_overflow 0
		.amdhsa_tg_split 0
		.amdhsa_exception_fp_ieee_invalid_op 0
		.amdhsa_exception_fp_denorm_src 0
		.amdhsa_exception_fp_ieee_div_zero 0
		.amdhsa_exception_fp_ieee_overflow 0
		.amdhsa_exception_fp_ieee_underflow 0
		.amdhsa_exception_fp_ieee_inexact 0
		.amdhsa_exception_int_div_zero 0
	.end_amdhsa_kernel

amdhsa.kernels:
  - .agpr_count:     0
    .args:
      - .offset:         0
        .size:           336
        .value_kind:     by_value
      - .offset:         336
        .size:           4
        .value_kind:     hidden_block_count_x
      - .offset:         340
        .size:           4
        .value_kind:     hidden_block_count_y
      - .offset:         344
        .size:           4
        .value_kind:     hidden_block_count_z
      - .offset:         348
        .size:           2
        .value_kind:     hidden_group_size_x
      - .offset:         350
        .size:           2
        .value_kind:     hidden_group_size_y
      - .offset:         352
        .size:           2
        .value_kind:     hidden_group_size_z
      - .offset:         354
        .size:           2
        .value_kind:     hidden_remainder_x
      - .offset:         356
        .size:           2
        .value_kind:     hidden_remainder_y
      - .offset:         358
        .size:           2
        .value_kind:     hidden_remainder_z
      - .offset:         376
        .size:           8
        .value_kind:     hidden_global_offset_x
      - .offset:         384
        .size:           8
        .value_kind:     hidden_global_offset_y
      - .offset:         392
        .size:           8
        .value_kind:     hidden_global_offset_z
      - .offset:         400
        .size:           2
        .value_kind:     hidden_grid_dims
      - .offset:         456
        .size:           4
        .value_kind:     hidden_dynamic_lds_size
    .group_segment_fixed_size: 0
    .kernarg_segment_align: 8
    .kernarg_segment_size: 592
    .language:       OpenCL C
    .language_version:
      - 2
      - 0
    .max_flat_workgroup_size: 512
    .name:           _Z10fwd_kernel4Args
    .private_segment_fixed_size: 0
    .sgpr_count:     105
    .sgpr_spill_count: 133
    .symbol:         _Z10fwd_kernel4Args.kd
    .uniform_work_group_size: 1
    .uses_dynamic_stack: false
    .vgpr_count:     256
    .vgpr_spill_count: 0
    .wavefront_size: 64
